# stack 2: + hand-written W_out/W_fc1/W_fc2 weight transposes (all nine tiles prefetched before the W_in transpose, one barrier per tile, cvt_pk)
# baseline (speedup 1.0000x reference)
.LBB0_302:
	s_or_b64 exec, exec, s[28:29]
	v_readlane_b32 s0, v253, 29
	v_readlane_b32 s1, v253, 30
	v_mov_b32_e32 v0, v179
	s_andn2_b64 vcc, exec, s[0:1]
	s_waitcnt vmcnt(0) lgkmcnt(0)
	s_barrier
	s_sub_u32 s24, s74, 0xb0
	s_subb_u32 s25, s75, 0
	s_load_dword s20, s[74:75], 0x0
	s_load_dwordx4 s[56:59], s[24:25], 0x70
	s_load_dwordx4 s[92:95], s[24:25], 0x80
	s_waitcnt lgkmcnt(0)
	s_cmp_eq_u32 s20, 0x100
	s_cbranch_scc0 .Ltp_nopref
	v_lshrrev_b32_e32 v40, 4, v179
	v_and_b32_e32 v41, 15, v179
	v_lshlrev_b32_e32 v41, 4, v41
	v_lshl_add_u32 v42, v40, 12, v41
	v_lshl_add_u32 v43, v40, 14, v41
	v_and_b32_e32 v40, 7, v179
	v_lshlrev_b32_e32 v40, 5, v40
	s_and_b32 s0, s96, 15
	s_lshr_b32 s1, s96, 4
	s_and_b32 s2, s96, 63
	s_lshr_b32 s3, s96, 6
	s_lshl_b32 s6, s0, 18
	s_lshl_b32 s9, s1, 8
	s_add_u32 s6, s6, s9
	s_add_u32 s48, s56, s6
	s_addc_u32 s49, s57, 0
	s_add_u32 s44, s48, 0x20000
	s_addc_u32 s45, s49, 0
	global_load_dwordx4 v[44:47], v42, s[48:49]
	global_load_dwordx4 v[48:51], v42, s[44:45]
	s_lshl_b32 s6, s0, 20
	s_add_u32 s9, s1, 0
	s_lshl_b32 s9, s9, 8
	s_add_u32 s6, s6, s9
	s_add_u32 s48, s92, s6
	s_addc_u32 s49, s93, 0
	s_add_u32 s44, s48, 0x80000
	s_addc_u32 s45, s49, 0
	global_load_dwordx4 v[52:55], v43, s[48:49]
	global_load_dwordx4 v[56:59], v43, s[44:45]
	s_lshl_b32 s6, s0, 20
	s_add_u32 s9, s1, 16
	s_lshl_b32 s9, s9, 8
	s_add_u32 s6, s6, s9
	s_add_u32 s48, s92, s6
	s_addc_u32 s49, s93, 0
	s_add_u32 s44, s48, 0x80000
	s_addc_u32 s45, s49, 0
	global_load_dwordx4 v[60:63], v43, s[48:49]
	global_load_dwordx4 v[64:67], v43, s[44:45]
	s_lshl_b32 s6, s0, 20
	s_add_u32 s9, s1, 32
	s_lshl_b32 s9, s9, 8
	s_add_u32 s6, s6, s9
	s_add_u32 s48, s92, s6
	s_addc_u32 s49, s93, 0
	s_add_u32 s44, s48, 0x80000
	s_addc_u32 s45, s49, 0
	global_load_dwordx4 v[68:71], v43, s[48:49]
	global_load_dwordx4 v[72:75], v43, s[44:45]
	s_lshl_b32 s6, s0, 20
	s_add_u32 s9, s1, 48
	s_lshl_b32 s9, s9, 8
	s_add_u32 s6, s6, s9
	s_add_u32 s48, s92, s6
	s_addc_u32 s49, s93, 0
	s_add_u32 s44, s48, 0x80000
	s_addc_u32 s45, s49, 0
	global_load_dwordx4 v[76:79], v43, s[48:49]
	global_load_dwordx4 v[80:83], v43, s[44:45]
	s_lshl_b32 s6, s2, 18
	s_add_u32 s9, s3, 0
	s_lshl_b32 s9, s9, 8
	s_add_u32 s6, s6, s9
	s_add_u32 s48, s94, s6
	s_addc_u32 s49, s95, 0
	s_add_u32 s44, s48, 0x20000
	s_addc_u32 s45, s49, 0
	global_load_dwordx4 v[84:87], v42, s[48:49]
	global_load_dwordx4 v[88:91], v42, s[44:45]
	s_lshl_b32 s6, s2, 18
	s_add_u32 s9, s3, 4
	s_lshl_b32 s9, s9, 8
	s_add_u32 s6, s6, s9
	s_add_u32 s48, s94, s6
	s_addc_u32 s49, s95, 0
	s_add_u32 s44, s48, 0x20000
	s_addc_u32 s45, s49, 0
	global_load_dwordx4 v[92:95], v42, s[48:49]
	global_load_dwordx4 v[96:99], v42, s[44:45]
	s_lshl_b32 s6, s2, 18
	s_add_u32 s9, s3, 8
	s_lshl_b32 s9, s9, 8
	s_add_u32 s6, s6, s9
	s_add_u32 s48, s94, s6
	s_addc_u32 s49, s95, 0
	s_add_u32 s44, s48, 0x20000
	s_addc_u32 s45, s49, 0
	global_load_dwordx4 v[100:103], v42, s[48:49]
	global_load_dwordx4 v[104:107], v42, s[44:45]
	s_lshl_b32 s6, s2, 18
	s_add_u32 s9, s3, 12
	s_lshl_b32 s9, s9, 8
	s_add_u32 s6, s6, s9
	s_add_u32 s48, s94, s6
	s_addc_u32 s49, s95, 0
	s_add_u32 s44, s48, 0x20000
	s_addc_u32 s45, s49, 0
	global_load_dwordx4 v[108:111], v42, s[48:49]
	global_load_dwordx4 v[112:115], v42, s[44:45]
	s_lshl_b32 s6, s0, 8
	s_add_u32 s48, s58, s6
	s_addc_u32 s49, s59, 0
	global_load_dwordx4 v[116:119], v40, s[48:49]
	global_load_dwordx4 v[120:123], v40, s[48:49] offset:16
.Ltp_nopref:
	s_cbranch_vccnz .LBB0_321
	v_ashrrev_i32_e32 v23, 4, v0
	v_readlane_b32 s0, v253, 44
	v_lshlrev_b32_e32 v1, 2, v0
	v_and_b32_e32 v4, 60, v1
	v_add_u32_e32 v2, s0, v23
	v_ashrrev_i32_e32 v3, 31, v2
	v_readlane_b32 s0, v253, 45
	v_lshlrev_b64 v[2:3], 13, v[2:3]
	v_readlane_b32 s1, v253, 46
	v_lshlrev_b32_e32 v176, 2, v4
	v_ashrrev_i32_e32 v31, 3, v0
	v_lshl_add_u64 v[2:3], s[0:1], 0, v[2:3]
	v_lshl_add_u64 v[2:3], v[2:3], 0, v[176:177]
	v_add_co_u32_e32 v6, vcc, 0x40000, v2
	s_movk_i32 s0, 0x104
	s_nop 0
	v_addc_co_u32_e32 v7, vcc, 0, v3, vcc
	global_load_dwordx4 v[8:11], v[2:3], off
	global_load_dwordx4 v[12:15], v[6:7], off
	v_lshlrev_b32_e32 v0, 3, v0
	v_mul_lo_u32 v1, v23, s0
	v_and_b32_e32 v0, 56, v0
	v_add3_u32 v30, 0, v1, v176
	v_lshl_add_u32 v1, v31, 2, 0
	v_xor_b32_e32 v32, 32, v31
	v_mul_u32_u24_e32 v2, 0x104, v0
	v_cmp_lt_i32_e64 s[38:39], 32, v31
	v_mad_u32_u24 v33, v0, s0, 0
	v_lshlrev_b32_e32 v34, 1, v32
	v_lshlrev_b32_e32 v35, 1, v31
	v_lshlrev_b32_e32 v16, 2, v4
	v_add_u32_e32 v36, v1, v2
	v_lshlrev_b32_e32 v176, 1, v0
	s_mov_b32 s3, s96
	s_branch .LBB0_306

.LBB0_321:
	v_readlane_b32 s0, v253, 47
	v_readlane_b32 s1, v253, 48
	v_mov_b32_e32 v0, v179
	s_andn2_b64 vcc, exec, s[0:1]
	v_cndmask_b32_e64 v1, 0, 1, s[0:1]
	v_cmp_ne_u32_e64 s[38:39], 1, v1
	s_load_dword s20, s[74:75], 0x0
	s_waitcnt lgkmcnt(0)
	s_cmp_eq_u32 s20, 0x100
	s_cbranch_scc1 .Ltp_fast
	s_cbranch_vccnz .LBB0_340
	v_ashrrev_i32_e32 v23, 4, v0
	v_readlane_b32 s0, v253, 44
	v_lshlrev_b32_e32 v1, 2, v0
	v_and_b32_e32 v4, 60, v1
	v_add_u32_e32 v2, s0, v23
	v_ashrrev_i32_e32 v3, 31, v2
	v_readlane_b32 s0, v253, 49
	v_lshlrev_b64 v[2:3], 12, v[2:3]
	v_readlane_b32 s1, v253, 50
	v_lshlrev_b32_e32 v176, 2, v4
	v_ashrrev_i32_e32 v31, 3, v0
	v_lshl_add_u64 v[2:3], s[0:1], 0, v[2:3]
	v_lshl_add_u64 v[2:3], v[2:3], 0, v[176:177]
	v_add_co_u32_e32 v6, vcc, 0x20000, v2
	s_movk_i32 s0, 0x104
	s_nop 0
	v_addc_co_u32_e32 v7, vcc, 0, v3, vcc
	global_load_dwordx4 v[8:11], v[2:3], off
	global_load_dwordx4 v[12:15], v[6:7], off
	v_lshlrev_b32_e32 v0, 3, v0
	v_mul_lo_u32 v1, v23, s0
	v_and_b32_e32 v0, 56, v0
	v_add3_u32 v30, 0, v1, v176
	v_lshl_add_u32 v1, v31, 2, 0
	v_xor_b32_e32 v32, 32, v31
	v_mul_u32_u24_e32 v2, 0x104, v0
	v_cmp_lt_i32_e64 s[40:41], 32, v31
	v_mad_u32_u24 v33, v0, s0, 0
	v_lshlrev_b32_e32 v34, 1, v32
	v_lshlrev_b32_e32 v35, 1, v31
	v_lshlrev_b32_e32 v16, 2, v4
	v_add_u32_e32 v36, v1, v2
	v_lshlrev_b32_e32 v176, 1, v0
	s_mov_b32 s3, s96
	s_branch .LBB0_325

.LBB0_378:
	s_andn2_saveexec_b64 s[28:29], s[28:29]
	s_cbranch_execz .LBB0_371
	v_add_u32_e32 v22, v31, v5
	v_and_b32_e32 v22, 63, v22
	v_lshl_add_u32 v22, v22, 2, 0
	ds_read_b32 v22, v22 offset:16640
	s_branch .LBB0_371
	s_branch .LBB0_380
.Ltp_fast:
	s_sub_u32 s24, s74, 0xb0
	s_subb_u32 s25, s75, 0
	s_load_dwordx2 s[28:29], s[24:25], 0xa0
	v_lshrrev_b32_e32 v0, 4, v179
	v_and_b32_e32 v1, 15, v179
	v_lshrrev_b32_e32 v2, 3, v179
	v_and_b32_e32 v3, 7, v179
	s_movk_i32 s20, 0x104
	v_mul_u32_u24_e32 v4, s20, v0
	v_lshl_add_u32 v4, v1, 4, v4
	s_movk_i32 s20, 0x820
	v_mul_u32_u24_e32 v5, s20, v3
	v_lshl_add_u32 v5, v2, 2, v5
	v_add_u32_e32 v8, 0x4400, v4
	v_add_u32_e32 v9, 0x6480, v4
	v_add_u32_e32 v12, 0x4400, v5
	v_add_u32_e32 v13, 0x4810, v5
	v_add_u32_e32 v10, 0x0, v4
	v_add_u32_e32 v11, 0x2080, v4
	v_add_u32_e32 v14, 0x0, v5
	v_add_u32_e32 v15, 0x410, v5
	v_lshlrev_b32_e32 v6, 4, v3
	v_lshl_add_u32 v7, v2, 13, v6
	v_lshl_add_u32 v6, v2, 11, v6
	s_and_b32 s0, s96, 15
	s_lshr_b32 s1, s96, 4
	s_and_b32 s2, s96, 63
	s_lshr_b32 s3, s96, 6
	s_waitcnt vmcnt(0) lgkmcnt(0)
	s_lshl_b32 s6, s1, 17
	s_lshl_b32 s9, s0, 7
	s_add_u32 s6, s6, s9
	s_add_u32 s6, s6, 0x1c400000
	s_add_u32 s48, s28, s6
	s_addc_u32 s49, s29, 0
	ds_write2_b32 v8, v44, v45 offset1:1
	ds_write2_b32 v8, v46, v47 offset0:2 offset1:3
	ds_write2_b32 v9, v48, v49 offset1:1
	ds_write2_b32 v9, v50, v51 offset0:2 offset1:3
	s_waitcnt lgkmcnt(0)
	s_barrier
	ds_read2_b32 v[16:17], v12 offset1:65
	ds_read2_b32 v[18:19], v12 offset0:130 offset1:195
	ds_read2_b32 v[20:21], v13 offset1:65
	ds_read2_b32 v[22:23], v13 offset0:130 offset1:195
	s_waitcnt lgkmcnt(0)
	v_cvt_pk_bf16_f32 v24, v16, v17
	v_cvt_pk_bf16_f32 v25, v18, v19
	v_cvt_pk_bf16_f32 v26, v20, v21
	v_cvt_pk_bf16_f32 v27, v22, v23
	global_store_dwordx4 v6, v[24:27], s[48:49] sc1
	s_add_u32 s6, s1, 0
	s_lshl_b32 s6, s6, 17
	s_lshl_b32 s9, s0, 7
	s_add_u32 s6, s6, s9
	s_add_u32 s6, s6, 0x1c600000
	s_add_u32 s48, s28, s6
	s_addc_u32 s49, s29, 0
	ds_write2_b32 v10, v52, v53 offset1:1
	ds_write2_b32 v10, v54, v55 offset0:2 offset1:3
	ds_write2_b32 v11, v56, v57 offset1:1
	ds_write2_b32 v11, v58, v59 offset0:2 offset1:3
	s_waitcnt lgkmcnt(0)
	s_barrier
	ds_read2_b32 v[16:17], v14 offset1:65
	ds_read2_b32 v[18:19], v14 offset0:130 offset1:195
	ds_read2_b32 v[20:21], v15 offset1:65
	ds_read2_b32 v[22:23], v15 offset0:130 offset1:195
	s_waitcnt lgkmcnt(0)
	v_mul_f32_e32 v16, v16, v116
	v_mul_f32_e32 v17, v17, v117
	v_mul_f32_e32 v18, v18, v118
	v_mul_f32_e32 v19, v19, v119
	v_mul_f32_e32 v20, v20, v120
	v_mul_f32_e32 v21, v21, v121
	v_mul_f32_e32 v22, v22, v122
	v_mul_f32_e32 v23, v23, v123
	v_cvt_pk_bf16_f32 v28, v16, v17
	v_cvt_pk_bf16_f32 v29, v18, v19
	v_cvt_pk_bf16_f32 v30, v20, v21
	v_cvt_pk_bf16_f32 v31, v22, v23
	global_store_dwordx4 v6, v[28:31], s[48:49] sc1
	s_add_u32 s6, s1, 16
	s_lshl_b32 s6, s6, 17
	s_lshl_b32 s9, s0, 7
	s_add_u32 s6, s6, s9
	s_add_u32 s6, s6, 0x1c600000
	s_add_u32 s48, s28, s6
	s_addc_u32 s49, s29, 0
	ds_write2_b32 v8, v60, v61 offset1:1
	ds_write2_b32 v8, v62, v63 offset0:2 offset1:3
	ds_write2_b32 v9, v64, v65 offset1:1
	ds_write2_b32 v9, v66, v67 offset0:2 offset1:3
	s_waitcnt lgkmcnt(0)
	s_barrier
	ds_read2_b32 v[16:17], v12 offset1:65
	ds_read2_b32 v[18:19], v12 offset0:130 offset1:195
	ds_read2_b32 v[20:21], v13 offset1:65
	ds_read2_b32 v[22:23], v13 offset0:130 offset1:195
	s_waitcnt lgkmcnt(0)
	v_mul_f32_e32 v16, v16, v116
	v_mul_f32_e32 v17, v17, v117
	v_mul_f32_e32 v18, v18, v118
	v_mul_f32_e32 v19, v19, v119
	v_mul_f32_e32 v20, v20, v120
	v_mul_f32_e32 v21, v21, v121
	v_mul_f32_e32 v22, v22, v122
	v_mul_f32_e32 v23, v23, v123
	v_cvt_pk_bf16_f32 v24, v16, v17
	v_cvt_pk_bf16_f32 v25, v18, v19
	v_cvt_pk_bf16_f32 v26, v20, v21
	v_cvt_pk_bf16_f32 v27, v22, v23
	global_store_dwordx4 v6, v[24:27], s[48:49] sc1
	s_add_u32 s6, s1, 32
	s_lshl_b32 s6, s6, 17
	s_lshl_b32 s9, s0, 7
	s_add_u32 s6, s6, s9
	s_add_u32 s6, s6, 0x1c600000
	s_add_u32 s48, s28, s6
	s_addc_u32 s49, s29, 0
	ds_write2_b32 v10, v68, v69 offset1:1
	ds_write2_b32 v10, v70, v71 offset0:2 offset1:3
	ds_write2_b32 v11, v72, v73 offset1:1
	ds_write2_b32 v11, v74, v75 offset0:2 offset1:3
	s_waitcnt lgkmcnt(0)
	s_barrier
	ds_read2_b32 v[16:17], v14 offset1:65
	ds_read2_b32 v[18:19], v14 offset0:130 offset1:195
	ds_read2_b32 v[20:21], v15 offset1:65
	ds_read2_b32 v[22:23], v15 offset0:130 offset1:195
	s_waitcnt lgkmcnt(0)
	v_mul_f32_e32 v16, v16, v116
	v_mul_f32_e32 v17, v17, v117
	v_mul_f32_e32 v18, v18, v118
	v_mul_f32_e32 v19, v19, v119
	v_mul_f32_e32 v20, v20, v120
	v_mul_f32_e32 v21, v21, v121
	v_mul_f32_e32 v22, v22, v122
	v_mul_f32_e32 v23, v23, v123
	v_cvt_pk_bf16_f32 v28, v16, v17
	v_cvt_pk_bf16_f32 v29, v18, v19
	v_cvt_pk_bf16_f32 v30, v20, v21
	v_cvt_pk_bf16_f32 v31, v22, v23
	global_store_dwordx4 v6, v[28:31], s[48:49] sc1
	s_add_u32 s6, s1, 48
	s_lshl_b32 s6, s6, 17
	s_lshl_b32 s9, s0, 7
	s_add_u32 s6, s6, s9
	s_add_u32 s6, s6, 0x1c600000
	s_add_u32 s48, s28, s6
	s_addc_u32 s49, s29, 0
	ds_write2_b32 v8, v76, v77 offset1:1
	ds_write2_b32 v8, v78, v79 offset0:2 offset1:3
	ds_write2_b32 v9, v80, v81 offset1:1
	ds_write2_b32 v9, v82, v83 offset0:2 offset1:3
	s_waitcnt lgkmcnt(0)
	s_barrier
	ds_read2_b32 v[16:17], v12 offset1:65
	ds_read2_b32 v[18:19], v12 offset0:130 offset1:195
	ds_read2_b32 v[20:21], v13 offset1:65
	ds_read2_b32 v[22:23], v13 offset0:130 offset1:195
	s_waitcnt lgkmcnt(0)
	v_mul_f32_e32 v16, v16, v116
	v_mul_f32_e32 v17, v17, v117
	v_mul_f32_e32 v18, v18, v118
	v_mul_f32_e32 v19, v19, v119
	v_mul_f32_e32 v20, v20, v120
	v_mul_f32_e32 v21, v21, v121
	v_mul_f32_e32 v22, v22, v122
	v_mul_f32_e32 v23, v23, v123
	v_cvt_pk_bf16_f32 v24, v16, v17
	v_cvt_pk_bf16_f32 v25, v18, v19
	v_cvt_pk_bf16_f32 v26, v20, v21
	v_cvt_pk_bf16_f32 v27, v22, v23
	global_store_dwordx4 v6, v[24:27], s[48:49] sc1
	s_add_u32 s6, s3, 0
	s_lshl_b32 s6, s6, 19
	s_lshl_b32 s9, s2, 7
	s_add_u32 s6, s6, s9
	s_add_u32 s6, s6, 0x1ce00000
	s_add_u32 s48, s28, s6
	s_addc_u32 s49, s29, 0
	ds_write2_b32 v10, v84, v85 offset1:1
	ds_write2_b32 v10, v86, v87 offset0:2 offset1:3
	ds_write2_b32 v11, v88, v89 offset1:1
	ds_write2_b32 v11, v90, v91 offset0:2 offset1:3
	s_waitcnt lgkmcnt(0)
	s_barrier
	ds_read2_b32 v[16:17], v14 offset1:65
	ds_read2_b32 v[18:19], v14 offset0:130 offset1:195
	ds_read2_b32 v[20:21], v15 offset1:65
	ds_read2_b32 v[22:23], v15 offset0:130 offset1:195
	s_waitcnt lgkmcnt(0)
	v_cvt_pk_bf16_f32 v28, v16, v17
	v_cvt_pk_bf16_f32 v29, v18, v19
	v_cvt_pk_bf16_f32 v30, v20, v21
	v_cvt_pk_bf16_f32 v31, v22, v23
	global_store_dwordx4 v7, v[28:31], s[48:49] sc1
	s_add_u32 s6, s3, 4
	s_lshl_b32 s6, s6, 19
	s_lshl_b32 s9, s2, 7
	s_add_u32 s6, s6, s9
	s_add_u32 s6, s6, 0x1ce00000
	s_add_u32 s48, s28, s6
	s_addc_u32 s49, s29, 0
	ds_write2_b32 v8, v92, v93 offset1:1
	ds_write2_b32 v8, v94, v95 offset0:2 offset1:3
	ds_write2_b32 v9, v96, v97 offset1:1
	ds_write2_b32 v9, v98, v99 offset0:2 offset1:3
	s_waitcnt lgkmcnt(0)
	s_barrier
	ds_read2_b32 v[16:17], v12 offset1:65
	ds_read2_b32 v[18:19], v12 offset0:130 offset1:195
	ds_read2_b32 v[20:21], v13 offset1:65
	ds_read2_b32 v[22:23], v13 offset0:130 offset1:195
	s_waitcnt lgkmcnt(0)
	v_cvt_pk_bf16_f32 v24, v16, v17
	v_cvt_pk_bf16_f32 v25, v18, v19
	v_cvt_pk_bf16_f32 v26, v20, v21
	v_cvt_pk_bf16_f32 v27, v22, v23
	global_store_dwordx4 v7, v[24:27], s[48:49] sc1
	s_add_u32 s6, s3, 8
	s_lshl_b32 s6, s6, 19
	s_lshl_b32 s9, s2, 7
	s_add_u32 s6, s6, s9
	s_add_u32 s6, s6, 0x1ce00000
	s_add_u32 s48, s28, s6
	s_addc_u32 s49, s29, 0
	ds_write2_b32 v10, v100, v101 offset1:1
	ds_write2_b32 v10, v102, v103 offset0:2 offset1:3
	ds_write2_b32 v11, v104, v105 offset1:1
	ds_write2_b32 v11, v106, v107 offset0:2 offset1:3
	s_waitcnt lgkmcnt(0)
	s_barrier
	ds_read2_b32 v[16:17], v14 offset1:65
	ds_read2_b32 v[18:19], v14 offset0:130 offset1:195
	ds_read2_b32 v[20:21], v15 offset1:65
	ds_read2_b32 v[22:23], v15 offset0:130 offset1:195
	s_waitcnt lgkmcnt(0)
	v_cvt_pk_bf16_f32 v28, v16, v17
	v_cvt_pk_bf16_f32 v29, v18, v19
	v_cvt_pk_bf16_f32 v30, v20, v21
	v_cvt_pk_bf16_f32 v31, v22, v23
	global_store_dwordx4 v7, v[28:31], s[48:49] sc1
	s_add_u32 s6, s3, 12
	s_lshl_b32 s6, s6, 19
	s_lshl_b32 s9, s2, 7
	s_add_u32 s6, s6, s9
	s_add_u32 s6, s6, 0x1ce00000
	s_add_u32 s48, s28, s6
	s_addc_u32 s49, s29, 0
	ds_write2_b32 v8, v108, v109 offset1:1
	ds_write2_b32 v8, v110, v111 offset0:2 offset1:3
	ds_write2_b32 v9, v112, v113 offset1:1
	ds_write2_b32 v9, v114, v115 offset0:2 offset1:3
	s_waitcnt lgkmcnt(0)
	s_barrier
	ds_read2_b32 v[16:17], v12 offset1:65
	ds_read2_b32 v[18:19], v12 offset0:130 offset1:195
	ds_read2_b32 v[20:21], v13 offset1:65
	ds_read2_b32 v[22:23], v13 offset0:130 offset1:195
	s_waitcnt lgkmcnt(0)
	v_cvt_pk_bf16_f32 v24, v16, v17
	v_cvt_pk_bf16_f32 v25, v18, v19
	v_cvt_pk_bf16_f32 v26, v20, v21
	v_cvt_pk_bf16_f32 v27, v22, v23
	global_store_dwordx4 v7, v[24:27], s[48:49] sc1
	s_branch .LBB0_380
